# v83 + even-B: dropped 10 dead v_readlane per iteration (SMP_LOAD reloads a spilled 16-SGPR tuple but reads only s[84:87])
# speedup vs baseline: 1.0034x; 1.0034x over previous
; DI void smp_load(SmpKV& R, const float* ck, const float* cv, int phys, int pos0, int hg, int lane) {
;     const size_t base = ((size_t)phys * PAGE + pos0) * SBW + hg * 256 + lane * 4;
; #pragma unroll
;     for (int u = 0; u < 4; ++u) { R.k[u] = __builtin_nontemporal_load((const f32x4*)(ck + base + (size_t)u * SBW)); R.v[u] = __builtin_nontemporal_load((const f32x4*)(cv + base + (size_t)u * SBW)); }
; }
.LBB0_578:
	v_readlane_b32 s6, v242, 9
	s_min_i32 s12, s6, 61
	s_add_i32 s14, s12, 2
	s_ashr_i32 s12, s14, 5
	s_sub_i32 s64, 1, s12
	s_lshl_b64 s[12:13], s[64:65], 2
	v_readlane_b32 s6, v242, 7
	v_readlane_b32 s7, v242, 8
	s_add_u32 s12, s6, s12
	s_addc_u32 s13, s7, s13
	s_load_dword s12, s[12:13], 0x0
	s_not_b32 s13, s14
	s_lshl_b32 s13, s13, 11
	s_and_b32 s14, s13, 0xf800
	s_waitcnt lgkmcnt(0)
	s_ashr_i32 s13, s12, 31
	s_lshl_b64 s[12:13], s[12:13], 16
	s_or_b32 s12, s12, s14
	v_mov_b32_e32 v5, s13
	v_or_b32_e32 v4, s12, v200
	v_lshlrev_b64 v[4:5], 2, v[4:5]
	v_readlane_b32 s84, v244, 15
	v_readlane_b32 s85, v244, 16
	v_readlane_b32 s86, v244, 17
	v_readlane_b32 s87, v244, 18
	v_lshl_add_u64 v[40:41], s[84:85], 0, v[4:5]
	s_movk_i32 s6, 0x1000
	v_lshl_add_u64 v[4:5], s[86:87], 0, v[4:5]
	global_load_dwordx4 v[88:91], v[40:41], off nt
	global_load_dwordx4 v[112:115], v[40:41], off offset:2048 nt
	global_load_dwordx4 v[92:95], v[4:5], off nt
	global_load_dwordx4 v[104:107], v[4:5], off offset:2048 nt
	v_add_co_u32_e32 v40, vcc, s6, v40
	v_readlane_b32 s81, v244, 12
	s_nop 0
	v_addc_co_u32_e32 v41, vcc, 0, v41, vcc
	v_add_co_u32_e32 v4, vcc, 0x1000, v4
	v_readlane_b32 s82, v244, 13
	s_nop 0
	v_addc_co_u32_e32 v5, vcc, 0, v5, vcc
	global_load_dwordx4 v[128:131], v[40:41], off nt
	global_load_dwordx4 v[144:147], v[40:41], off offset:2048 nt
	global_load_dwordx4 v[120:123], v[4:5], off nt
	global_load_dwordx4 v[136:139], v[4:5], off offset:2048 nt
	s_and_b64 vcc, exec, s[18:19]
	s_mov_b64 s[14:15], 0
	s_barrier
	s_cbranch_vccnz .LBB0_582
	s_cmp_gt_i32 s75, 0
	s_mov_b64 s[12:13], -1
	s_cbranch_scc1 .LBB0_581
	s_lshl_b32 s12, s72, 12
	s_add_i32 s12, s12, s74
	v_add_u32_e32 v4, s12, v191
	v_ashrrev_i32_e32 v5, 31, v4
	v_lshlrev_b64 v[4:5], 11, v[4:5]
	v_lshl_add_u64 v[4:5], s[16:17], 0, v[4:5]
	s_lshl_b32 s64, s73, 7
	v_lshl_add_u64 v[4:5], v[4:5], 0, s[64:65]
	v_lshlrev_b32_e32 v40, 1, v206
	v_mov_b32_e32 v41, v2
	v_lshl_add_u64 v[4:5], v[4:5], 0, v[40:41]
	v_cvt_pk_bf16_f32 v40, v6, v7
	v_cvt_pk_bf16_f32 v41, v8, v9
	global_store_dwordx2 v[4:5], v[40:41], off
	v_cvt_pk_bf16_f32 v40, v10, v11
	v_cvt_pk_bf16_f32 v41, v12, v13
	global_store_dwordx2 v[4:5], v[40:41], off offset:16
	v_cvt_pk_bf16_f32 v40, v14, v15
	v_cvt_pk_bf16_f32 v41, v16, v17
	global_store_dwordx2 v[4:5], v[40:41], off offset:32
	v_cvt_pk_bf16_f32 v40, v18, v19
	v_cvt_pk_bf16_f32 v41, v20, v21
	global_store_dwordx2 v[4:5], v[40:41], off offset:48
	v_cvt_pk_bf16_f32 v40, v22, v23
	v_cvt_pk_bf16_f32 v41, v24, v25
	global_store_dwordx2 v[4:5], v[40:41], off offset:64
	v_cvt_pk_bf16_f32 v40, v26, v27
	v_cvt_pk_bf16_f32 v41, v28, v29
	global_store_dwordx2 v[4:5], v[40:41], off offset:80
	v_cvt_pk_bf16_f32 v40, v30, v31
	v_cvt_pk_bf16_f32 v41, v32, v33
	global_store_dwordx2 v[4:5], v[40:41], off offset:96
	v_cvt_pk_bf16_f32 v40, v34, v35
	v_cvt_pk_bf16_f32 v41, v36, v37
	s_mov_b64 s[12:13], 0
	global_store_dwordx2 v[4:5], v[40:41], off offset:112

; DI void smp_load(SmpKV& R, const float* ck, const float* cv, int phys, int pos0, int hg, int lane) {
;     const size_t base = ((size_t)phys * PAGE + pos0) * SBW + hg * 256 + lane * 4;
; #pragma unroll
;     for (int u = 0; u < 4; ++u) { R.k[u] = __builtin_nontemporal_load((const f32x4*)(ck + base + (size_t)u * SBW)); R.v[u] = __builtin_nontemporal_load((const f32x4*)(cv + base + (size_t)u * SBW)); }
; }
.LBB0_642:
	v_readlane_b32 s6, v242, 9
	s_min_i32 s12, s6, 61
	s_add_i32 s14, s12, 2
	s_ashr_i32 s12, s14, 5
	s_sub_i32 s64, 1, s12
	s_lshl_b64 s[12:13], s[64:65], 2
	v_readlane_b32 s6, v242, 7
	v_readlane_b32 s7, v242, 8
	s_add_u32 s12, s6, s12
	s_addc_u32 s13, s7, s13
	s_load_dword s12, s[12:13], 0x0
	s_not_b32 s13, s14
	s_lshl_b32 s13, s13, 11
	s_and_b32 s14, s13, 0xf800
	s_waitcnt lgkmcnt(0)
	s_ashr_i32 s13, s12, 31
	s_lshl_b64 s[12:13], s[12:13], 16
	s_or_b32 s12, s12, s14
	v_mov_b32_e32 v5, s13
	v_or_b32_e32 v4, s12, v200
	v_lshlrev_b64 v[4:5], 2, v[4:5]
	v_readlane_b32 s84, v244, 15
	v_readlane_b32 s85, v244, 16
	v_readlane_b32 s86, v244, 17
	v_readlane_b32 s87, v244, 18
	v_lshl_add_u64 v[40:41], s[84:85], 0, v[4:5]
	s_movk_i32 s6, 0x1000
	v_lshl_add_u64 v[4:5], s[86:87], 0, v[4:5]
	global_load_dwordx4 v[100:103], v[40:41], off nt
	global_load_dwordx4 v[116:119], v[40:41], off offset:2048 nt
	global_load_dwordx4 v[96:99], v[4:5], off nt
	global_load_dwordx4 v[108:111], v[4:5], off offset:2048 nt
	v_add_co_u32_e32 v40, vcc, s6, v40
	v_readlane_b32 s81, v244, 12
	s_nop 0
	v_addc_co_u32_e32 v41, vcc, 0, v41, vcc
	v_add_co_u32_e32 v4, vcc, 0x1000, v4
	v_readlane_b32 s82, v244, 13
	s_nop 0
	v_addc_co_u32_e32 v5, vcc, 0, v5, vcc
	global_load_dwordx4 v[132:135], v[40:41], off nt
	global_load_dwordx4 v[148:151], v[40:41], off offset:2048 nt
	global_load_dwordx4 v[124:127], v[4:5], off nt
	global_load_dwordx4 v[140:143], v[4:5], off offset:2048 nt
	s_and_b64 vcc, exec, s[18:19]
	s_mov_b64 s[6:7], 0
	s_barrier
	s_cbranch_vccnz .LBB0_647
	s_cmp_gt_i32 s75, 0
	s_mov_b64 s[60:61], -1
	s_cbranch_scc1 .LBB0_645
	s_lshl_b32 s12, s72, 12
	s_add_i32 s12, s12, s74
	v_add_u32_e32 v4, s12, v191
	v_ashrrev_i32_e32 v5, 31, v4
	v_lshlrev_b64 v[4:5], 11, v[4:5]
	v_lshl_add_u64 v[4:5], s[16:17], 0, v[4:5]
	s_lshl_b32 s64, s73, 7
	v_lshl_add_u64 v[4:5], v[4:5], 0, s[64:65]
	v_lshlrev_b32_e32 v40, 1, v206
	v_mov_b32_e32 v41, v2
	v_lshl_add_u64 v[4:5], v[4:5], 0, v[40:41]
	v_cvt_pk_bf16_f32 v40, v6, v7
	v_cvt_pk_bf16_f32 v41, v8, v9
	global_store_dwordx2 v[4:5], v[40:41], off
	v_cvt_pk_bf16_f32 v40, v10, v11
	v_cvt_pk_bf16_f32 v41, v12, v13
	global_store_dwordx2 v[4:5], v[40:41], off offset:16
	v_cvt_pk_bf16_f32 v40, v14, v15
	v_cvt_pk_bf16_f32 v41, v16, v17
	global_store_dwordx2 v[4:5], v[40:41], off offset:32
	v_cvt_pk_bf16_f32 v40, v18, v19
	v_cvt_pk_bf16_f32 v41, v20, v21
	global_store_dwordx2 v[4:5], v[40:41], off offset:48
	v_cvt_pk_bf16_f32 v40, v22, v23
	v_cvt_pk_bf16_f32 v41, v24, v25
	global_store_dwordx2 v[4:5], v[40:41], off offset:64
	v_cvt_pk_bf16_f32 v40, v26, v27
	v_cvt_pk_bf16_f32 v41, v28, v29
	global_store_dwordx2 v[4:5], v[40:41], off offset:80
	v_cvt_pk_bf16_f32 v40, v30, v31
	v_cvt_pk_bf16_f32 v41, v32, v33
	global_store_dwordx2 v[4:5], v[40:41], off offset:96
	v_cvt_pk_bf16_f32 v40, v34, v35
	v_cvt_pk_bf16_f32 v41, v36, v37
	s_mov_b64 s[60:61], 0
	global_store_dwordx2 v[4:5], v[40:41], off offset:112
